# first seam (after the prologue phase) uses the same two-level XCD barrier as the other 13 seams instead of the cooperative-groups grid sync
# speedup vs baseline: 1.0785x; 1.0143x over previous
; __device__ __forceinline__ unsigned xb_ld(unsigned* p)              { return __hip_atomic_load(p, __ATOMIC_RELAXED, __HIP_MEMORY_SCOPE_AGENT); }
; __device__ __forceinline__ unsigned xb_add(unsigned* p, unsigned v) { return __hip_atomic_fetch_add(p, v, __ATOMIC_RELAXED, __HIP_MEMORY_SCOPE_AGENT); }
; __device__ __forceinline__ void xcd_barrier_complete(unsigned* bar, unsigned x, unsigned& nloc, unsigned& nx) {
;     const unsigned G = gridDim.x * gridDim.y * gridDim.z;
;     unsigned sum, cnt, mine, sp = 0u;
;     for (;;) {
;         sum = 0u; cnt = 0u; mine = 0u;
; #pragma unroll
;         for (unsigned j = 0; j < 16; ++j) { const unsigned c = xb_ld(&bar[XB_XCNT(j)]); sum += c; cnt += (c > 0u) ? 1u : 0u; mine = (j == x) ? c : mine; }
; __device__ __forceinline__ void xcd_barrier(const XcdBarrier& b, const int tid_) {
;     asm volatile("s_waitcnt vmcnt(0)" ::: "memory");
;     __syncthreads();
;     if (tid_ == 0) {
;         unsigned* bar = b.bar;
;         __builtin_amdgcn_s_waitcnt(0);
;         unsigned nloc = b.st[0], nx = b.st[1];
;         if (nloc == 0u) { xcd_barrier_complete(bar, b.x, nloc, nx); b.st[0] = nloc; b.st[1] = nx; }
;         const unsigned old = xb_add(&bar[XB_XSUB(b.x)], 1u);
.LBB0_103:
	v_readlane_b32 s0, v254, 1
	v_readlane_b32 s1, v254, 2
	s_cmp_gt_i32 s1, 1
	s_cselect_b64 s[0:1], -1, 0
	s_and_b64 s[2:3], s[6:7], s[0:1]
	s_andn2_b64 vcc, exec, s[2:3]
	s_cbranch_vccnz .LBB0_115
	s_mov_b64 s[4:5], s[82:83]
	v_mbcnt_lo_u32_b32 v0, -1, 0
	v_mbcnt_hi_u32_b32 v0, -1, v0
	s_getreg_b32 s6, hwreg(HW_REG_XCC_ID, 0, 4)
	s_waitcnt vmcnt(0)
	v_sub_u32_e32 v0, 0, v0
	v_cmp_eq_u32_e32 vcc, s52, v0
	s_waitcnt vmcnt(0) lgkmcnt(0)
	s_barrier
	s_and_saveexec_b64 s[2:3], vcc
	s_cbranch_execz .Lmy_s0_223
	s_add_i32 s7, 0, 0x23fc0
	v_mov_b32_e32 v0, s7
	s_load_dwordx2 s[4:5], s[4:5], 0xc8
	s_waitcnt vmcnt(0) expcnt(0) lgkmcnt(0)
	ds_read_b32 v2, v0
	s_add_i32 s7, 0, 0x23fc4
	v_mov_b32_e32 v0, s7
	ds_read_b32 v0, v0
	s_and_b32 s33, s6, 15
	s_waitcnt lgkmcnt(1)
	v_cmp_ne_u32_e32 vcc, 0, v2
	s_cbranch_vccnz .Lmy_s0_187
	s_load_dword s6, s[82:83], 0xe0
	s_mov_b32 s49, 1
	v_mov_b32_e32 v16, 0
	s_waitcnt lgkmcnt(0)
	s_mul_i32 s48, s55, s6
	s_add_u32 s6, s4, 0x1900200
	s_addc_u32 s7, s5, 0
	s_add_u32 s8, s4, 0x1900400
	s_addc_u32 s9, s5, 0
	s_add_u32 s10, s4, 0x1900500
	s_addc_u32 s11, s5, 0
	s_add_u32 s12, s4, 0x1900600
	s_addc_u32 s13, s5, 0
	s_add_u32 s14, s4, 0x1900700
	s_addc_u32 s15, s5, 0
	s_add_u32 s16, s4, 0x1900800
	s_addc_u32 s17, s5, 0
	s_add_u32 s18, s4, 0x1900900
	s_addc_u32 s19, s5, 0
	s_add_u32 s20, s4, 0x1900a00
	s_addc_u32 s21, s5, 0
	s_add_u32 s22, s4, 0x1900b00
	s_addc_u32 s23, s5, 0
	s_add_u32 s24, s4, 0x1900c00
	s_addc_u32 s25, s5, 0
	s_add_u32 s26, s4, 0x1900d00
	s_addc_u32 s27, s5, 0
	s_add_u32 s28, s4, 0x1900e00
	s_addc_u32 s29, s5, 0
	s_add_u32 s30, s4, 0x1900f00
	s_addc_u32 s31, s5, 0
	s_add_u32 s34, s4, 0x1901000
	s_addc_u32 s35, s5, 0
	s_add_u32 s36, s4, 0x1901100
	s_addc_u32 s37, s5, 0
	s_add_u32 s38, s4, 0x1901200
	s_addc_u32 s39, s5, 0
	s_add_u32 s40, s4, 0x1901300
	s_mul_i32 s48, s48, s54
	s_addc_u32 s41, s5, 0
	s_branch .Lmy_s0_175

; #define TID() int lane_v_; asm volatile("v_mbcnt_lo_u32_b32 %0, -1, 0\n\tv_mbcnt_hi_u32_b32 %0, -1, %0" : "=v"(lane_v_)); const int tid = wave_s * 64 + lane_v_
; #define PTRS() kptr_t kp = kargs(); unsigned char* ws = kws(kp); (void)ws
;     __host__ __device__ bool next(int i, Unit& u) const {
;         const long L = (long)i * G + c; if (L >= nwg) return false;
;         int wgid = (int)L; { const int q = nwg / NXCD, r = nwg % NXCD, xcd = wgid % NXCD, off = wgid / NXCD; wgid = (xcd < r ? xcd * (q + 1) : r * (q + 1) + (xcd - r) * q) + off; }
;         const int nig = wgm * nN, gid = wgid / nig, fm = gid * wgm, gsz = (nM - fm) < wgm ? (nM - fm) : wgm;
;         u.pm = fm + ((wgid % nig) % gsz); u.pn = (wgid % nig) / gsz; return true;
; __global__ void __launch_bounds__(NTHR, 2) hybrid_fwd(Args a) {
;     ...
;     if (IN(1)) for (int rep_ = 0; rep_ < REPS(1); ++rep_) { TID(); PTRS();
;         { pg8::Gemm g{S1, (const bf16_t*)(ws + WS_WQKVZ), M, ATT_IN, D}; pg8::StaticOrder S; S.init(M, ATT_IN, G, bid);
;           pg8::EpiQKVZ E{QKVZ, (const float*)(ws + WS_BIAS), (const float*)(ws + WS_COS), (const float*)(ws + WS_SIN)};
;           pg8::gemm_phase<pg8::EpiQKVZ, pg8::StaticOrder, true, true>(lds, g, S, E, tid); }
.Lmy_s0_223:
	s_or_b64 exec, exec, s[2:3]
	s_waitcnt lgkmcnt(0)
	s_barrier
.LBB0_115:
	v_readlane_b32 s2, v254, 1
	v_readlane_b32 s3, v254, 2
	s_cmp_lt_i32 s2, 2
	s_cselect_b64 s[2:3], -1, 0
	s_and_b64 s[6:7], s[2:3], s[0:1]
	s_andn2_b64 vcc, exec, s[6:7]
	v_writelane_b32 v254, s52, 3
	s_cbranch_vccnz .LBB0_170
	s_cmpk_lt_i32 s84, 0x500
	s_cselect_b64 s[0:1], -1, 0
	s_ashr_i32 s50, s84, 31
	s_lshr_b32 s2, s50, 29
	s_add_i32 s2, s84, s2
	s_ashr_i32 s33, s2, 3
	s_and_b32 s2, s2, -8
	s_sub_i32 s38, s84, s2
	s_mov_b64 s[2:3], s[82:83]
	v_mbcnt_lo_u32_b32 v172, -1, 0
	v_mbcnt_hi_u32_b32 v172, -1, v172
	s_load_dwordx2 s[8:9], s[2:3], 0xc8
	s_cmp_lt_i32 s38, 0
	v_add_u32_e32 v176, s52, v172
	s_waitcnt lgkmcnt(0)
	s_cselect_b64 s[10:11], -1, 0
	s_cmpk_gt_i32 s84, 0x4ff
	v_readfirstlane_b32 s2, v176
	s_cbranch_scc1 .LBB0_118
	s_movk_i32 s3, 0xa1
	s_and_b64 s[4:5], s[10:11], exec
	s_cselect_b32 s3, s3, 0xa0
	s_mul_i32 s3, s38, s3
	s_add_i32 s3, s3, s33
	s_mul_hi_i32 s4, s3, 0x88888889
	s_add_i32 s4, s4, s3
	s_lshr_b32 s5, s4, 31
	s_ashr_i32 s4, s4, 6
	s_add_i32 s4, s4, s5
	s_mul_i32 s12, s4, 12
	s_sub_i32 s5, 0x80, s12
	s_mulk_i32 s4, 0x78
	s_min_u32 s13, s5, 12
	s_sub_i32 s3, s3, s4
	s_sext_i32_i8 s4, s3
	v_cvt_f32_ubyte0_e32 v1, s13
	v_cvt_f32_i32_e32 v0, s4
	v_rcp_iflag_f32_e32 v2, v1
	s_ashr_i32 s4, s4, 30
	s_or_b32 s14, s4, 1
	v_mul_f32_e32 v2, v0, v2
	v_trunc_f32_e32 v2, v2
	v_fma_f32 v0, -v2, v1, v0
	v_cvt_i32_f32_e32 v2, v2
	v_cmp_ge_f32_e64 s[4:5], |v0|, v1
	s_and_b64 s[4:5], s[4:5], exec
	s_cselect_b32 s4, s14, 0
	v_readfirstlane_b32 s5, v2
	s_add_i32 s5, s5, s4
	s_sext_i32_i8 s4, s5
	s_mul_i32 s5, s5, s13
	s_sub_i32 s3, s3, s5
	s_sext_i32_i8 s3, s3
	s_add_i32 s30, s12, s3
